# up-GEMM conv-gate epilogue: hoisted one weight wait before the 8 row blocks, removed per-block vmcnt(0) and tile-start drain; plus pipelined EpiRes epilogue
# speedup vs baseline: 1.0011x; 1.0011x over previous
;     ...
;         const bool has_next = S.next(ui + 1, nxt);
;         const char* nA = has_next ? (const char*)g.A + (size_t)nxt.pm * tstepA : cA; const char* nB = has_next ? (const char*)g.Bt + (size_t)nxt.pn * tstepB : cB;
;     ...
; #pragma unroll
;         for (int a = 0; a < 2; ++a)
; #pragma unroll
;             for (int b = 0; b < 2; ++b)
; #pragma unroll
;                 for (int m = 0; m < 4; ++m)
; #pragma unroll
;                     for (int n = 0; n < 2; ++n) acc[a][b][m][n] = (f32x4){0.f, 0.f, 0.f, 0.f};
;         cur = nxt; cA = nA; cB = nB; ++ui;
.LBB0_805:
	s_ashr_i32 s21, s20, 31
	s_lshl_b64 s[24:25], s[20:21], 19
	s_add_u32 s24, s35, s24
	s_addc_u32 s25, s36, s25
	s_and_b64 s[0:1], s[0:1], exec
	s_cselect_b32 s21, s25, s29
	s_cselect_b32 s27, s24, s28
	s_add_u32 s0, s30, 0x3e080
	s_addc_u32 s1, s31, 0
	s_add_u32 s81, s28, 0x100
	v_mov_b32_e32 v0, 0
	s_addc_u32 s86, s29, 0
	s_mov_b32 vcc_lo, -2
	v_mov_b32_e32 v1, v0
	v_mov_b32_e32 v2, v0
	v_mov_b32_e32 v3, v0
	v_mov_b32_e32 v4, v0
	v_mov_b32_e32 v5, v0
	v_mov_b32_e32 v6, v0
	v_mov_b32_e32 v7, v0
	v_mov_b32_e32 v16, v0
	v_mov_b32_e32 v17, v0
	v_mov_b32_e32 v18, v0
	v_mov_b32_e32 v19, v0
	v_mov_b32_e32 v20, v0
	v_mov_b32_e32 v21, v0
	v_mov_b32_e32 v22, v0
	v_mov_b32_e32 v23, v0
	s_nop 0
	v_mov_b32_e32 v32, v0
	v_mov_b32_e32 v33, v0
	v_mov_b32_e32 v34, v0
	v_mov_b32_e32 v35, v0
	v_mov_b32_e32 v36, v0
	v_mov_b32_e32 v37, v0
	v_mov_b32_e32 v38, v0
	v_mov_b32_e32 v39, v0
	v_mov_b32_e32 v48, v0
	v_mov_b32_e32 v49, v0
	v_mov_b32_e32 v50, v0
	v_mov_b32_e32 v51, v0
	v_mov_b32_e32 v52, v0
	v_mov_b32_e32 v53, v0
	v_mov_b32_e32 v54, v0
	v_mov_b32_e32 v55, v0
	v_mov_b32_e32 v8, v0
	v_mov_b32_e32 v9, v0
	v_mov_b32_e32 v10, v0
	v_mov_b32_e32 v11, v0
	v_mov_b32_e32 v12, v0
	v_mov_b32_e32 v13, v0
	v_mov_b32_e32 v14, v0
	v_mov_b32_e32 v15, v0
	v_mov_b32_e32 v24, v0
	v_mov_b32_e32 v25, v0
	v_mov_b32_e32 v26, v0
	v_mov_b32_e32 v27, v0
	v_mov_b32_e32 v28, v0
	v_mov_b32_e32 v29, v0
	v_mov_b32_e32 v30, v0
	v_mov_b32_e32 v31, v0
	v_mov_b32_e32 v40, v0
	v_mov_b32_e32 v41, v0
	v_mov_b32_e32 v42, v0
	v_mov_b32_e32 v43, v0
	v_mov_b32_e32 v44, v0
	v_mov_b32_e32 v45, v0
	v_mov_b32_e32 v46, v0
	v_mov_b32_e32 v47, v0
	v_mov_b32_e32 v56, v0
	v_mov_b32_e32 v57, v0
	v_mov_b32_e32 v58, v0
	v_mov_b32_e32 v59, v0
	v_mov_b32_e32 v60, v0
	v_mov_b32_e32 v61, v0
	v_mov_b32_e32 v62, v0
	v_mov_b32_e32 v63, v0
	v_mov_b32_e32 v88, v0
	v_mov_b32_e32 v89, v0
	v_mov_b32_e32 v90, v0
	v_mov_b32_e32 v91, v0
	v_mov_b32_e32 v100, v0
	v_mov_b32_e32 v101, v0
	v_mov_b32_e32 v102, v0
	v_mov_b32_e32 v103, v0
	v_mov_b32_e32 v112, v0
	v_mov_b32_e32 v113, v0
	v_mov_b32_e32 v114, v0
	v_mov_b32_e32 v115, v0
	v_mov_b32_e32 v116, v0
	v_mov_b32_e32 v117, v0
	v_mov_b32_e32 v118, v0
	v_mov_b32_e32 v119, v0
	v_mov_b32_e32 v128, v0
	v_mov_b32_e32 v129, v0
	v_mov_b32_e32 v130, v0
	v_mov_b32_e32 v131, v0
	v_mov_b32_e32 v132, v0
	v_mov_b32_e32 v133, v0
	v_mov_b32_e32 v134, v0
	v_mov_b32_e32 v135, v0
	v_mov_b32_e32 v144, v0
	v_mov_b32_e32 v145, v0
	v_mov_b32_e32 v146, v0
	v_mov_b32_e32 v147, v0
	v_mov_b32_e32 v148, v0
	v_mov_b32_e32 v149, v0
	v_mov_b32_e32 v150, v0
	v_mov_b32_e32 v151, v0
	v_mov_b32_e32 v104, v0
	v_mov_b32_e32 v105, v0
	v_mov_b32_e32 v106, v0
	v_mov_b32_e32 v107, v0
	v_mov_b32_e32 v108, v0
	v_mov_b32_e32 v109, v0
	v_mov_b32_e32 v110, v0
	v_mov_b32_e32 v111, v0
	v_mov_b32_e32 v120, v0
	v_mov_b32_e32 v121, v0
	v_mov_b32_e32 v122, v0
	v_mov_b32_e32 v123, v0
	v_mov_b32_e32 v124, v0
	v_mov_b32_e32 v125, v0
	v_mov_b32_e32 v126, v0
	v_mov_b32_e32 v127, v0
	v_mov_b32_e32 v136, v0
	v_mov_b32_e32 v137, v0
	v_mov_b32_e32 v138, v0
	v_mov_b32_e32 v139, v0
	v_mov_b32_e32 v140, v0
	v_mov_b32_e32 v141, v0
	v_mov_b32_e32 v142, v0
	v_mov_b32_e32 v143, v0
	v_mov_b32_e32 v152, v0
	v_mov_b32_e32 v153, v0
	v_mov_b32_e32 v154, v0
	v_mov_b32_e32 v155, v0
	v_mov_b32_e32 v156, v0
	v_mov_b32_e32 v157, v0
	v_mov_b32_e32 v158, v0
	v_mov_b32_e32 v159, v0

; __device__ __forceinline__ unsigned cvt_pk_bf16(float lo, float hi) { const f32x2_t v = {lo, hi}; return __builtin_bit_cast(unsigned, __builtin_convertvector(v, bf16x2_t)); }
;     __device__ __forceinline__ void operator()(const f32x4 (&acc)[2][2][4][2], const Unit& u, int wr, int wc, int fr, int fq) const {
;         const int lane = threadIdx.x & 63;
;         const int col0 = u.pn * 128 + wc * 32 + 8 * fq;
;         f32x4 w0[2], w1[2], w2[2], bb[2];
; #pragma unroll
;         for (int n = 0; n < 2; ++n) { w0[n] = *(const f32x4*)(cw + col0 + 4 * n); w1[n] = *(const f32x4*)(cw + 2816 + col0 + 4 * n); w2[n] = *(const f32x4*)(cw + 2 * 2816 + col0 + 4 * n); bb[n] = *(const f32x4*)(cb + col0 + 4 * n); }
; #pragma unroll
;         for (int ai = 0; ai < 2; ++ai) {
;             const int gbase = u.pm * 248 + 62 * (2 * ai + wr) - 2;
;             float r1[2][4], r2[2][4];
; #pragma unroll
;             for (int n = 0; n < 2; ++n)
; #pragma unroll
;                 for (int x = 0; x < 4; ++x) { r1[n][x] = 0.f; r2[n][x] = 0.f; }
; #pragma unroll
;             for (int m = 0; m < 4; ++m) {
;                 const int rl = 16 * m + fr, g = gbase + rl, tt = g & 16383;
;                 unsigned pk[4];
; #pragma unroll
;                 for (int n = 0; n < 2; ++n) {
;                     float a[4];
; #pragma unroll
;                     for (int x = 0; x < 4; ++x) {
;                         const float uu = acc[ai][0][m][n][x];
;                         float p1 = PG8_DPP(r1[n][x], uu, 0x111);
;                         float p2 = PG8_DPP(r2[n][x], uu, 0x112);
;                         r1[n][x] = PG8_DPP(0.f, uu, 0x121); r2[n][x] = PG8_DPP(0.f, uu, 0x122);
;                         if (tt < 1) p1 = 0.f;
;                         if (tt < 2) p2 = 0.f;
;                         const float uc = bb[n][x] + w2[n][x] * uu + w1[n][x] * p1 + w0[n][x] * p2;
;                         const float sg = __builtin_amdgcn_rcpf(1.f + __builtin_amdgcn_exp2f(-1.44269504f * uc));
;                         a[x] = uc * sg * acc[ai][1][m][n][x];
;                     }
;                     pk[2 * n] = cvt_pk_bf16(a[0], a[1]); pk[2 * n + 1] = cvt_pk_bf16(a[2], a[3]);
;                 }
;                 if (rl >= 2 && g < Mrows) { u32x4 w; w.x = pk[0]; w.y = pk[1]; w.z = pk[2]; w.w = pk[3]; *(u32x4*)(O + (size_t)g * 2816 + col0) = w; }
.LBB0_809:
	v_lshl_or_b32 v180, s26, 7, v203
	v_ashrrev_i32_e32 v181, 31, v180
	v_lshlrev_b64 v[64:65], 2, v[180:181]
	v_lshl_add_u64 v[68:69], s[10:11], 0, v[64:65]
	v_lshl_add_u64 v[72:73], s[14:15], 0, v[64:65]
	v_lshl_add_u64 v[76:77], s[16:17], 0, v[64:65]
	v_lshl_add_u64 v[96:97], s[12:13], 0, v[64:65]
	global_load_dwordx4 v[64:67], v[68:69], off offset:16
	global_load_dwordx4 v[80:83], v[68:69], off
	s_nop 0
	global_load_dwordx4 v[68:71], v[72:73], off offset:16
	global_load_dwordx4 v[84:87], v[72:73], off
	s_nop 0
	global_load_dwordx4 v[72:75], v[76:77], off offset:16
	global_load_dwordx4 v[92:95], v[76:77], off
	s_nop 0
	global_load_dwordx4 v[76:79], v[96:97], off offset:16
	s_nop 0
	global_load_dwordx4 v[96:99], v[96:97], off
	s_mul_i32 s21, s80, 0xf8
	s_add_i32 s21, s21, s67
	v_add_u32_e32 v221, s21, v182
	s_mov_b32 s28, 0x8000
	v_mov_b32_e32 v234, v161
	v_mov_b32_e32 v235, v161
	v_mov_b32_e32 v217, v161
	v_mov_b32_e32 v218, v161
	v_mov_b32_e32 v236, v161
	v_mov_b32_e32 v237, v161
	v_mov_b32_e32 v219, v161
	v_mov_b32_e32 v220, v161
	v_mov_b32_e32 v230, v161
	v_mov_b32_e32 v231, v161
	v_mov_b32_e32 v213, v161
	v_mov_b32_e32 v214, v161
	v_mov_b32_e32 v232, v161
	v_mov_b32_e32 v233, v161
	v_mov_b32_e32 v215, v161
	v_mov_b32_e32 v216, v161
	v_mov_b32_e32 v226, v161
	v_mov_b32_e32 v227, v161
	v_mov_b32_e32 v209, v161
	v_mov_b32_e32 v210, v161
	v_mov_b32_e32 v228, v161
	v_mov_b32_e32 v229, v161
	v_mov_b32_e32 v211, v161
	v_mov_b32_e32 v212, v161
	v_mov_b32_e32 v222, v161
	v_mov_b32_e32 v223, v161
	v_mov_b32_e32 v205, v161
	v_mov_b32_e32 v206, v161
	v_mov_b32_e32 v224, v161
	v_mov_b32_e32 v225, v161
	v_mov_b32_e32 v207, v161
	v_mov_b32_e32 v208, v161
	v_cmp_gt_i32_e32 vcc, s28, v221
	v_mov_b32_dpp v234, v156 row_shr:1 row_mask:0xf bank_mask:0xf
	v_mov_b32_dpp v235, v156 row_shr:2 row_mask:0xf bank_mask:0xf
	v_mov_b32_dpp v217, v156 row_ror:1 row_mask:0xf bank_mask:0xf
	v_mov_b32_dpp v218, v156 row_ror:2 row_mask:0xf bank_mask:0xf
	v_mov_b32_dpp v236, v157 row_shr:1 row_mask:0xf bank_mask:0xf
	v_mov_b32_dpp v237, v157 row_shr:2 row_mask:0xf bank_mask:0xf
	v_mov_b32_dpp v219, v157 row_ror:1 row_mask:0xf bank_mask:0xf
	v_mov_b32_dpp v220, v157 row_ror:2 row_mask:0xf bank_mask:0xf
	v_mov_b32_dpp v230, v158 row_shr:1 row_mask:0xf bank_mask:0xf
	v_mov_b32_dpp v231, v158 row_shr:2 row_mask:0xf bank_mask:0xf
	v_mov_b32_dpp v213, v158 row_ror:1 row_mask:0xf bank_mask:0xf
	v_mov_b32_dpp v214, v158 row_ror:2 row_mask:0xf bank_mask:0xf
	v_mov_b32_dpp v232, v159 row_shr:1 row_mask:0xf bank_mask:0xf
	v_mov_b32_dpp v233, v159 row_shr:2 row_mask:0xf bank_mask:0xf
	v_mov_b32_dpp v215, v159 row_ror:1 row_mask:0xf bank_mask:0xf
	v_mov_b32_dpp v216, v159 row_ror:2 row_mask:0xf bank_mask:0xf
	v_mov_b32_dpp v226, v152 row_shr:1 row_mask:0xf bank_mask:0xf
	v_mov_b32_dpp v227, v152 row_shr:2 row_mask:0xf bank_mask:0xf
	v_mov_b32_dpp v209, v152 row_ror:1 row_mask:0xf bank_mask:0xf
	v_mov_b32_dpp v210, v152 row_ror:2 row_mask:0xf bank_mask:0xf
	v_mov_b32_dpp v228, v153 row_shr:1 row_mask:0xf bank_mask:0xf
	v_mov_b32_dpp v229, v153 row_shr:2 row_mask:0xf bank_mask:0xf
	v_mov_b32_dpp v211, v153 row_ror:1 row_mask:0xf bank_mask:0xf
	v_mov_b32_dpp v212, v153 row_ror:2 row_mask:0xf bank_mask:0xf
	v_mov_b32_dpp v222, v154 row_shr:1 row_mask:0xf bank_mask:0xf
	v_mov_b32_dpp v223, v154 row_shr:2 row_mask:0xf bank_mask:0xf
	v_mov_b32_dpp v205, v154 row_ror:1 row_mask:0xf bank_mask:0xf
	v_mov_b32_dpp v206, v154 row_ror:2 row_mask:0xf bank_mask:0xf
	v_mov_b32_dpp v224, v155 row_shr:1 row_mask:0xf bank_mask:0xf
	v_mov_b32_dpp v225, v155 row_shr:2 row_mask:0xf bank_mask:0xf
	v_mov_b32_dpp v207, v155 row_ror:1 row_mask:0xf bank_mask:0xf
	v_mov_b32_dpp v208, v155 row_ror:2 row_mask:0xf bank_mask:0xf
	s_waitcnt vmcnt(0)
	s_and_b64 s[0:1], s[4:5], vcc
	s_and_saveexec_b64 s[26:27], s[0:1]
	s_mov_b32 s86, 0x43160000
	s_movk_i32 s29, 0x1600
	s_cbranch_execz .LBB0_811
	v_and_b32_e32 v195, 0x3fff, v221
	v_cmp_gt_u32_e64 s[0:1], 2, v195
	v_cmp_eq_u32_e32 vcc, 0, v195
	s_nop 0
	v_pk_fma_f32 v[156:157], v[156:157], v[92:93], v[96:97]
	v_cndmask_b32_e64 v238, v235, 0, s[0:1]
	v_cndmask_b32_e64 v235, v236, 0, vcc
	v_cndmask_b32_e64 v234, v234, 0, vcc
	v_cndmask_b32_e64 v239, v237, 0, s[0:1]
	v_pk_fma_f32 v[156:157], v[84:85], v[234:235], v[156:157]
	v_pk_fma_f32 v[158:159], v[158:159], v[94:95], v[98:99]
	v_pk_fma_f32 v[156:157], v[80:81], v[238:239], v[156:157]
	v_cndmask_b32_e64 v236, v231, 0, s[0:1]
	v_mul_f32_e32 v195, 0xbfb8aa3b, v156
	v_exp_f32_e32 v195, v195
	v_mul_f32_e32 v196, 0xbfb8aa3b, v157
	v_exp_f32_e32 v196, v196
	v_cndmask_b32_e64 v231, v232, 0, vcc
	v_cndmask_b32_e64 v230, v230, 0, vcc
	v_cndmask_b32_e64 v237, v233, 0, s[0:1]
	v_pk_fma_f32 v[158:159], v[86:87], v[230:231], v[158:159]
	v_add_f32_e32 v195, 1.0, v195
	v_pk_fma_f32 v[158:159], v[82:83], v[236:237], v[158:159]
	v_rcp_f32_e32 v234, v195
	v_add_f32_e32 v195, 1.0, v196
	v_mul_f32_e32 v196, 0xbfb8aa3b, v158
	v_exp_f32_e32 v196, v196
	v_mul_f32_e32 v197, 0xbfb8aa3b, v159
	v_exp_f32_e32 v197, v197
	v_rcp_f32_e32 v235, v195
	v_add_f32_e32 v195, 1.0, v196
	v_rcp_f32_e32 v230, v195
	v_add_f32_e32 v195, 1.0, v197
	v_rcp_f32_e32 v231, v195
	v_pk_mul_f32 v[156:157], v[156:157], v[234:235]
	v_pk_fma_f32 v[152:153], v[152:153], v[72:73], v[76:77]
	v_pk_mul_f32 v[148:149], v[148:149], v[156:157]
	v_pk_mul_f32 v[156:157], v[158:159], v[230:231]
	v_cvt_pk_bf16_f32 v148, v148, v149
	v_pk_mul_f32 v[150:151], v[150:151], v[156:157]
	v_cndmask_b32_e64 v157, v228, 0, vcc
	v_cndmask_b32_e64 v156, v226, 0, vcc
	v_cvt_pk_bf16_f32 v149, v150, v151
	v_cndmask_b32_e64 v151, v229, 0, s[0:1]
	v_cndmask_b32_e64 v150, v227, 0, s[0:1]
; __device__ __forceinline__ unsigned cvt_pk_bf16(float lo, float hi) { const f32x2_t v = {lo, hi}; return __builtin_bit_cast(unsigned, __builtin_convertvector(v, bf16x2_t)); }
; #define PG8_DPP(old, src, ctrl) __builtin_bit_cast(float, __builtin_amdgcn_update_dpp(__builtin_bit_cast(int, (float)(old)), __builtin_bit_cast(int, (float)(src)), (ctrl), 0xf, 0xf, false))
;     __device__ __forceinline__ void operator()(const f32x4 (&acc)[2][2][4][2], const Unit& u, int wr, int wc, int fr, int fq) const {
;     ...
;             for (int m = 0; m < 4; ++m) {
;                 const int rl = 16 * m + fr, g = gbase + rl, tt = g & 16383;
;                 unsigned pk[4];
; #pragma unroll
;                 for (int n = 0; n < 2; ++n) {
;                     float a[4];
; #pragma unroll
;                     for (int x = 0; x < 4; ++x) {
;                         const float uu = acc[ai][0][m][n][x];
;                         float p1 = PG8_DPP(r1[n][x], uu, 0x111);
;                         float p2 = PG8_DPP(r2[n][x], uu, 0x112);
;                         r1[n][x] = PG8_DPP(0.f, uu, 0x121); r2[n][x] = PG8_DPP(0.f, uu, 0x122);
;                         if (tt < 1) p1 = 0.f;
;                         if (tt < 2) p2 = 0.f;
;                         const float uc = bb[n][x] + w2[n][x] * uu + w1[n][x] * p1 + w0[n][x] * p2;
;                         const float sg = __builtin_amdgcn_rcpf(1.f + __builtin_amdgcn_exp2f(-1.44269504f * uc));
;                         a[x] = uc * sg * acc[ai][1][m][n][x];
;                     }
;                     pk[2 * n] = cvt_pk_bf16(a[0], a[1]); pk[2 * n + 1] = cvt_pk_bf16(a[2], a[3]);
;                 }
;                 if (rl >= 2 && g < Mrows) { u32x4 w; w.x = pk[0]; w.y = pk[1]; w.z = pk[2]; w.w = pk[3]; *(u32x4*)(O + (size_t)g * 2816 + col0) = w; }
	v_pk_fma_f32 v[152:153], v[68:69], v[156:157], v[152:153]
	v_cndmask_b32_e64 v159, v224, 0, vcc
	v_pk_fma_f32 v[150:151], v[64:65], v[150:151], v[152:153]
	v_cndmask_b32_e64 v158, v222, 0, vcc
	v_mul_f32_e32 v152, 0xbfb8aa3b, v150
	v_exp_f32_e32 v156, v152
	v_mul_f32_e32 v152, 0xbfb8aa3b, v151
	v_exp_f32_e32 v157, v152
	v_pk_fma_f32 v[152:153], v[154:155], v[74:75], v[78:79]
	v_add_f32_e32 v154, 1.0, v156
	v_cndmask_b32_e64 v156, v223, 0, s[0:1]
	v_add_f32_e32 v155, 1.0, v157
	v_cndmask_b32_e64 v157, v225, 0, s[0:1]
	v_pk_fma_f32 v[152:153], v[70:71], v[158:159], v[152:153]
	v_rcp_f32_e32 v154, v154
	v_pk_fma_f32 v[152:153], v[66:67], v[156:157], v[152:153]
	v_rcp_f32_e32 v155, v155
	v_mul_f32_e32 v156, 0xbfb8aa3b, v152
	v_mul_f32_e32 v157, 0xbfb8aa3b, v153
	v_exp_f32_e32 v156, v156
	v_exp_f32_e32 v157, v157
	v_pk_mul_f32 v[150:151], v[150:151], v[154:155]
	v_add_f32_e32 v156, 1.0, v156
	v_add_f32_e32 v157, 1.0, v157
	v_rcp_f32_e32 v156, v156
	v_rcp_f32_e32 v157, v157
	v_pk_mul_f32 v[144:145], v[144:145], v[150:151]
	s_nop 0
	v_cvt_pk_bf16_f32 v150, v144, v145
	v_pk_mul_f32 v[144:145], v[152:153], v[156:157]
	s_nop 0
	v_pk_mul_f32 v[144:145], v[146:147], v[144:145]
	s_nop 0
	v_cvt_pk_bf16_f32 v151, v144, v145
	v_mov_b64_e32 v[144:145], s[60:61]
	v_mad_i64_i32 v[144:145], s[0:1], v221, s29, v[144:145]
	v_lshl_add_u64 v[144:145], v[180:181], 1, v[144:145]
	global_store_dwordx4 v[144:145], v[148:151], off
.LBB0_811:
	s_or_b64 exec, exec, s[26:27]
	v_add_u32_e32 v221, s21, v184
	v_mov_b32_e32 v156, v161
	v_mov_b32_e32 v157, v161
	v_mov_b32_e32 v158, v161
	v_mov_b32_e32 v159, v161
	v_mov_b32_e32 v152, v161
	v_mov_b32_e32 v153, v161
	v_mov_b32_e32 v154, v161
	v_mov_b32_e32 v155, v161
	v_mov_b32_e32 v148, v161
	v_mov_b32_e32 v149, v161
	v_mov_b32_e32 v150, v161
	v_mov_b32_e32 v151, v161
	v_mov_b32_e32 v144, v161
	v_mov_b32_e32 v145, v161
	v_mov_b32_e32 v146, v161
	v_mov_b32_e32 v147, v161
	v_mov_b32_dpp v217, v140 row_shr:1 row_mask:0xf bank_mask:0xf
	v_mov_b32_dpp v218, v140 row_shr:2 row_mask:0xf bank_mask:0xf
	v_mov_b32_dpp v156, v140 row_ror:1 row_mask:0xf bank_mask:0xf
	v_mov_b32_dpp v157, v140 row_ror:2 row_mask:0xf bank_mask:0xf
	v_mov_b32_dpp v219, v141 row_shr:1 row_mask:0xf bank_mask:0xf
	v_mov_b32_dpp v220, v141 row_shr:2 row_mask:0xf bank_mask:0xf
	v_mov_b32_dpp v158, v141 row_ror:1 row_mask:0xf bank_mask:0xf
	v_mov_b32_dpp v159, v141 row_ror:2 row_mask:0xf bank_mask:0xf
	v_mov_b32_dpp v213, v142 row_shr:1 row_mask:0xf bank_mask:0xf
	v_mov_b32_dpp v214, v142 row_shr:2 row_mask:0xf bank_mask:0xf
	v_mov_b32_dpp v152, v142 row_ror:1 row_mask:0xf bank_mask:0xf
	v_mov_b32_dpp v153, v142 row_ror:2 row_mask:0xf bank_mask:0xf
	v_mov_b32_dpp v215, v143 row_shr:1 row_mask:0xf bank_mask:0xf
	v_mov_b32_dpp v216, v143 row_shr:2 row_mask:0xf bank_mask:0xf
	v_mov_b32_dpp v154, v143 row_ror:1 row_mask:0xf bank_mask:0xf
	v_mov_b32_dpp v155, v143 row_ror:2 row_mask:0xf bank_mask:0xf
	v_mov_b32_dpp v209, v136 row_shr:1 row_mask:0xf bank_mask:0xf
	v_mov_b32_dpp v210, v136 row_shr:2 row_mask:0xf bank_mask:0xf
	v_mov_b32_dpp v148, v136 row_ror:1 row_mask:0xf bank_mask:0xf
	v_mov_b32_dpp v149, v136 row_ror:2 row_mask:0xf bank_mask:0xf
	v_mov_b32_dpp v211, v137 row_shr:1 row_mask:0xf bank_mask:0xf
	v_mov_b32_dpp v212, v137 row_shr:2 row_mask:0xf bank_mask:0xf
	v_mov_b32_dpp v150, v137 row_ror:1 row_mask:0xf bank_mask:0xf
	v_mov_b32_dpp v151, v137 row_ror:2 row_mask:0xf bank_mask:0xf
	v_mov_b32_dpp v205, v138 row_shr:1 row_mask:0xf bank_mask:0xf
	v_mov_b32_dpp v206, v138 row_shr:2 row_mask:0xf bank_mask:0xf
	v_mov_b32_dpp v144, v138 row_ror:1 row_mask:0xf bank_mask:0xf
	v_mov_b32_dpp v145, v138 row_ror:2 row_mask:0xf bank_mask:0xf
	v_mov_b32_dpp v207, v139 row_shr:1 row_mask:0xf bank_mask:0xf
	v_mov_b32_dpp v208, v139 row_shr:2 row_mask:0xf bank_mask:0xf
	v_mov_b32_dpp v146, v139 row_ror:1 row_mask:0xf bank_mask:0xf
	v_mov_b32_dpp v147, v139 row_ror:2 row_mask:0xf bank_mask:0xf
	v_cmp_gt_i32_e32 vcc, s28, v221
	s_and_saveexec_b64 s[26:27], vcc
	s_cbranch_execz .LBB0_813
	v_and_b32_e32 v195, 0x3fff, v221
	v_cmp_gt_u32_e64 s[0:1], 2, v195
	v_cmp_eq_u32_e32 vcc, 0, v195
	s_nop 0
	v_pk_fma_f32 v[140:141], v[140:141], v[92:93], v[96:97]
	v_cndmask_b32_e64 v222, v218, 0, s[0:1]
	v_cndmask_b32_e64 v219, v219, 0, vcc
	v_cndmask_b32_e64 v218, v217, 0, vcc
	v_cndmask_b32_e64 v223, v220, 0, s[0:1]
	v_pk_fma_f32 v[140:141], v[84:85], v[218:219], v[140:141]
	v_pk_fma_f32 v[142:143], v[142:143], v[94:95], v[98:99]
	v_pk_fma_f32 v[140:141], v[80:81], v[222:223], v[140:141]
	v_cndmask_b32_e64 v217, v216, 0, s[0:1]
	v_mul_f32_e32 v195, 0xbfb8aa3b, v140
	v_exp_f32_e32 v195, v195
	v_mul_f32_e32 v196, 0xbfb8aa3b, v141
	v_exp_f32_e32 v196, v196
	v_cndmask_b32_e64 v216, v214, 0, s[0:1]
	v_cndmask_b32_e64 v215, v215, 0, vcc
	v_cndmask_b32_e64 v214, v213, 0, vcc
	v_pk_fma_f32 v[142:143], v[86:87], v[214:215], v[142:143]
	v_add_f32_e32 v195, 1.0, v195
	v_pk_fma_f32 v[142:143], v[82:83], v[216:217], v[142:143]
	v_rcp_f32_e32 v218, v195
	v_add_f32_e32 v195, 1.0, v196
	v_mul_f32_e32 v196, 0xbfb8aa3b, v142
	v_exp_f32_e32 v196, v196
	v_mul_f32_e32 v197, 0xbfb8aa3b, v143
	v_exp_f32_e32 v197, v197
	v_rcp_f32_e32 v219, v195
	v_add_f32_e32 v195, 1.0, v196
	v_rcp_f32_e32 v214, v195
	v_add_f32_e32 v195, 1.0, v197
	v_rcp_f32_e32 v215, v195
	v_pk_mul_f32 v[140:141], v[140:141], v[218:219]
	v_pk_fma_f32 v[136:137], v[136:137], v[72:73], v[76:77]
	v_pk_mul_f32 v[132:133], v[132:133], v[140:141]
	v_pk_mul_f32 v[140:141], v[142:143], v[214:215]
	v_cvt_pk_bf16_f32 v132, v132, v133
	v_pk_mul_f32 v[134:135], v[134:135], v[140:141]
	v_cndmask_b32_e64 v141, v211, 0, vcc
	v_cndmask_b32_e64 v140, v209, 0, vcc
; __device__ __forceinline__ unsigned cvt_pk_bf16(float lo, float hi) { const f32x2_t v = {lo, hi}; return __builtin_bit_cast(unsigned, __builtin_convertvector(v, bf16x2_t)); }
; #define PG8_DPP(old, src, ctrl) __builtin_bit_cast(float, __builtin_amdgcn_update_dpp(__builtin_bit_cast(int, (float)(old)), __builtin_bit_cast(int, (float)(src)), (ctrl), 0xf, 0xf, false))
;     __device__ __forceinline__ void operator()(const f32x4 (&acc)[2][2][4][2], const Unit& u, int wr, int wc, int fr, int fq) const {
;     ...
;             for (int m = 0; m < 4; ++m) {
;                 const int rl = 16 * m + fr, g = gbase + rl, tt = g & 16383;
;                 unsigned pk[4];
; #pragma unroll
;                 for (int n = 0; n < 2; ++n) {
;                     float a[4];
; #pragma unroll
;                     for (int x = 0; x < 4; ++x) {
;                         const float uu = acc[ai][0][m][n][x];
;                         float p1 = PG8_DPP(r1[n][x], uu, 0x111);
;                         float p2 = PG8_DPP(r2[n][x], uu, 0x112);
;                         r1[n][x] = PG8_DPP(0.f, uu, 0x121); r2[n][x] = PG8_DPP(0.f, uu, 0x122);
;                         if (tt < 1) p1 = 0.f;
;                         if (tt < 2) p2 = 0.f;
;                         const float uc = bb[n][x] + w2[n][x] * uu + w1[n][x] * p1 + w0[n][x] * p2;
;                         const float sg = __builtin_amdgcn_rcpf(1.f + __builtin_amdgcn_exp2f(-1.44269504f * uc));
;                         a[x] = uc * sg * acc[ai][1][m][n][x];
;                     }
;                     pk[2 * n] = cvt_pk_bf16(a[0], a[1]); pk[2 * n + 1] = cvt_pk_bf16(a[2], a[3]);
;                 }
;                 if (rl >= 2 && g < Mrows) { u32x4 w; w.x = pk[0]; w.y = pk[1]; w.z = pk[2]; w.w = pk[3]; *(u32x4*)(O + (size_t)g * 2816 + col0) = w; }
	v_cvt_pk_bf16_f32 v133, v134, v135
	v_cndmask_b32_e64 v135, v212, 0, s[0:1]
	v_cndmask_b32_e64 v134, v210, 0, s[0:1]
	v_pk_fma_f32 v[136:137], v[68:69], v[140:141], v[136:137]
	v_cndmask_b32_e64 v143, v207, 0, vcc
	v_pk_fma_f32 v[134:135], v[64:65], v[134:135], v[136:137]
	v_cndmask_b32_e64 v142, v205, 0, vcc
	v_mul_f32_e32 v136, 0xbfb8aa3b, v134
	v_exp_f32_e32 v140, v136
	v_mul_f32_e32 v136, 0xbfb8aa3b, v135
	v_exp_f32_e32 v141, v136
	v_pk_fma_f32 v[136:137], v[138:139], v[74:75], v[78:79]
	v_add_f32_e32 v138, 1.0, v140
	v_cndmask_b32_e64 v140, v206, 0, s[0:1]
	v_add_f32_e32 v139, 1.0, v141
	v_cndmask_b32_e64 v141, v208, 0, s[0:1]
	v_pk_fma_f32 v[136:137], v[70:71], v[142:143], v[136:137]
	v_rcp_f32_e32 v138, v138
	v_pk_fma_f32 v[136:137], v[66:67], v[140:141], v[136:137]
	v_rcp_f32_e32 v139, v139
	v_mul_f32_e32 v140, 0xbfb8aa3b, v136
	v_mul_f32_e32 v141, 0xbfb8aa3b, v137
	v_exp_f32_e32 v140, v140
	v_exp_f32_e32 v141, v141
	v_pk_mul_f32 v[134:135], v[134:135], v[138:139]
	v_add_f32_e32 v140, 1.0, v140
	v_add_f32_e32 v141, 1.0, v141
	v_rcp_f32_e32 v140, v140
	v_rcp_f32_e32 v141, v141
	v_pk_mul_f32 v[128:129], v[128:129], v[134:135]
	s_nop 0
	v_cvt_pk_bf16_f32 v134, v128, v129
	v_pk_mul_f32 v[128:129], v[136:137], v[140:141]
	s_nop 0
	v_pk_mul_f32 v[128:129], v[130:131], v[128:129]
	s_nop 0
	v_cvt_pk_bf16_f32 v135, v128, v129
	v_mov_b64_e32 v[128:129], s[60:61]
	v_mad_i64_i32 v[128:129], s[0:1], v221, s29, v[128:129]
	v_lshl_add_u64 v[128:129], v[180:181], 1, v[128:129]
	global_store_dwordx4 v[128:129], v[132:135], off
.LBB0_813:
	s_or_b64 exec, exec, s[26:27]
	v_add_u32_e32 v205, s21, v185
	v_mov_b32_e32 v140, v161
	v_mov_b32_e32 v141, v161
	v_mov_b32_e32 v142, v161
	v_mov_b32_e32 v143, v161
	v_mov_b32_e32 v136, v161
	v_mov_b32_e32 v137, v161
	v_mov_b32_e32 v138, v161
	v_mov_b32_e32 v139, v161
	v_mov_b32_e32 v132, v161
	v_mov_b32_e32 v133, v161
	v_mov_b32_e32 v134, v161
	v_mov_b32_e32 v135, v161
	v_mov_b32_e32 v128, v161
	v_mov_b32_e32 v129, v161
	v_mov_b32_e32 v130, v161
	v_mov_b32_e32 v131, v161
	v_mov_b32_dpp v156, v124 row_shr:1 row_mask:0xf bank_mask:0xf
	v_mov_b32_dpp v157, v124 row_shr:2 row_mask:0xf bank_mask:0xf
	v_mov_b32_dpp v140, v124 row_ror:1 row_mask:0xf bank_mask:0xf
	v_mov_b32_dpp v141, v124 row_ror:2 row_mask:0xf bank_mask:0xf
	v_mov_b32_dpp v158, v125 row_shr:1 row_mask:0xf bank_mask:0xf
	v_mov_b32_dpp v159, v125 row_shr:2 row_mask:0xf bank_mask:0xf
	v_mov_b32_dpp v142, v125 row_ror:1 row_mask:0xf bank_mask:0xf
	v_mov_b32_dpp v143, v125 row_ror:2 row_mask:0xf bank_mask:0xf
	v_mov_b32_dpp v152, v126 row_shr:1 row_mask:0xf bank_mask:0xf
	v_mov_b32_dpp v153, v126 row_shr:2 row_mask:0xf bank_mask:0xf
	v_mov_b32_dpp v136, v126 row_ror:1 row_mask:0xf bank_mask:0xf
	v_mov_b32_dpp v137, v126 row_ror:2 row_mask:0xf bank_mask:0xf
	v_mov_b32_dpp v154, v127 row_shr:1 row_mask:0xf bank_mask:0xf
	v_mov_b32_dpp v155, v127 row_shr:2 row_mask:0xf bank_mask:0xf
	v_mov_b32_dpp v138, v127 row_ror:1 row_mask:0xf bank_mask:0xf
	v_mov_b32_dpp v139, v127 row_ror:2 row_mask:0xf bank_mask:0xf
	v_mov_b32_dpp v148, v120 row_shr:1 row_mask:0xf bank_mask:0xf
	v_mov_b32_dpp v149, v120 row_shr:2 row_mask:0xf bank_mask:0xf
	v_mov_b32_dpp v132, v120 row_ror:1 row_mask:0xf bank_mask:0xf
	v_mov_b32_dpp v133, v120 row_ror:2 row_mask:0xf bank_mask:0xf
	v_mov_b32_dpp v150, v121 row_shr:1 row_mask:0xf bank_mask:0xf
	v_mov_b32_dpp v151, v121 row_shr:2 row_mask:0xf bank_mask:0xf
	v_mov_b32_dpp v134, v121 row_ror:1 row_mask:0xf bank_mask:0xf
	v_mov_b32_dpp v135, v121 row_ror:2 row_mask:0xf bank_mask:0xf
	v_mov_b32_dpp v144, v122 row_shr:1 row_mask:0xf bank_mask:0xf
	v_mov_b32_dpp v145, v122 row_shr:2 row_mask:0xf bank_mask:0xf
	v_mov_b32_dpp v128, v122 row_ror:1 row_mask:0xf bank_mask:0xf
	v_mov_b32_dpp v129, v122 row_ror:2 row_mask:0xf bank_mask:0xf
	v_mov_b32_dpp v146, v123 row_shr:1 row_mask:0xf bank_mask:0xf
	v_mov_b32_dpp v147, v123 row_shr:2 row_mask:0xf bank_mask:0xf
	v_mov_b32_dpp v130, v123 row_ror:1 row_mask:0xf bank_mask:0xf
	v_mov_b32_dpp v131, v123 row_ror:2 row_mask:0xf bank_mask:0xf
	v_cmp_gt_i32_e32 vcc, s28, v205
	s_and_saveexec_b64 s[26:27], vcc
	s_cbranch_execz .LBB0_815
	v_and_b32_e32 v195, 0x3fff, v205
	v_cmp_gt_u32_e64 s[0:1], 2, v195
	v_cmp_eq_u32_e32 vcc, 0, v195
	s_nop 0
	v_pk_fma_f32 v[124:125], v[124:125], v[92:93], v[96:97]
	v_cndmask_b32_e64 v206, v157, 0, s[0:1]
	v_cndmask_b32_e64 v157, v158, 0, vcc
	v_cndmask_b32_e64 v156, v156, 0, vcc
	v_cndmask_b32_e64 v207, v159, 0, s[0:1]
	v_pk_fma_f32 v[124:125], v[84:85], v[156:157], v[124:125]
	v_pk_fma_f32 v[126:127], v[126:127], v[94:95], v[98:99]
	v_cndmask_b32_e64 v158, v153, 0, s[0:1]
	v_cndmask_b32_e64 v153, v154, 0, vcc
	v_cndmask_b32_e64 v152, v152, 0, vcc
	v_pk_fma_f32 v[124:125], v[80:81], v[206:207], v[124:125]
	v_cndmask_b32_e64 v159, v155, 0, s[0:1]
	v_pk_fma_f32 v[126:127], v[86:87], v[152:153], v[126:127]
	v_mul_f32_e32 v156, 0xbfb8aa3b, v124
	v_mul_f32_e32 v157, 0xbfb8aa3b, v125
	v_pk_fma_f32 v[126:127], v[82:83], v[158:159], v[126:127]
	v_exp_f32_e32 v156, v156
	v_exp_f32_e32 v157, v157
	v_mul_f32_e32 v152, 0xbfb8aa3b, v126
	v_mul_f32_e32 v153, 0xbfb8aa3b, v127
	v_exp_f32_e32 v152, v152
	v_exp_f32_e32 v153, v153
	v_add_f32_e32 v156, 1.0, v156
	v_add_f32_e32 v157, 1.0, v157
	v_rcp_f32_e32 v156, v156
	v_rcp_f32_e32 v157, v157
	v_add_f32_e32 v152, 1.0, v152
	v_add_f32_e32 v153, 1.0, v153
	v_rcp_f32_e32 v152, v152
	v_rcp_f32_e32 v153, v153
	v_pk_mul_f32 v[124:125], v[124:125], v[156:157]
	v_pk_fma_f32 v[120:121], v[120:121], v[72:73], v[76:77]
	v_pk_mul_f32 v[116:117], v[116:117], v[124:125]
	v_pk_mul_f32 v[124:125], v[126:127], v[152:153]
	v_cvt_pk_bf16_f32 v116, v116, v117
; __device__ __forceinline__ unsigned cvt_pk_bf16(float lo, float hi) { const f32x2_t v = {lo, hi}; return __builtin_bit_cast(unsigned, __builtin_convertvector(v, bf16x2_t)); }
; #define PG8_DPP(old, src, ctrl) __builtin_bit_cast(float, __builtin_amdgcn_update_dpp(__builtin_bit_cast(int, (float)(old)), __builtin_bit_cast(int, (float)(src)), (ctrl), 0xf, 0xf, false))
;     __device__ __forceinline__ void operator()(const f32x4 (&acc)[2][2][4][2], const Unit& u, int wr, int wc, int fr, int fq) const {
;     ...
;             for (int m = 0; m < 4; ++m) {
;                 const int rl = 16 * m + fr, g = gbase + rl, tt = g & 16383;
;                 unsigned pk[4];
; #pragma unroll
;                 for (int n = 0; n < 2; ++n) {
;                     float a[4];
; #pragma unroll
;                     for (int x = 0; x < 4; ++x) {
;                         const float uu = acc[ai][0][m][n][x];
;                         float p1 = PG8_DPP(r1[n][x], uu, 0x111);
;                         float p2 = PG8_DPP(r2[n][x], uu, 0x112);
;                         r1[n][x] = PG8_DPP(0.f, uu, 0x121); r2[n][x] = PG8_DPP(0.f, uu, 0x122);
;                         if (tt < 1) p1 = 0.f;
;                         if (tt < 2) p2 = 0.f;
;                         const float uc = bb[n][x] + w2[n][x] * uu + w1[n][x] * p1 + w0[n][x] * p2;
;                         const float sg = __builtin_amdgcn_rcpf(1.f + __builtin_amdgcn_exp2f(-1.44269504f * uc));
;                         a[x] = uc * sg * acc[ai][1][m][n][x];
;                     }
;                     pk[2 * n] = cvt_pk_bf16(a[0], a[1]); pk[2 * n + 1] = cvt_pk_bf16(a[2], a[3]);
;                 }
;                 if (rl >= 2 && g < Mrows) { u32x4 w; w.x = pk[0]; w.y = pk[1]; w.z = pk[2]; w.w = pk[3]; *(u32x4*)(O + (size_t)g * 2816 + col0) = w; }
	v_pk_mul_f32 v[118:119], v[118:119], v[124:125]
	v_cndmask_b32_e64 v125, v150, 0, vcc
	v_cndmask_b32_e64 v124, v148, 0, vcc
	v_cvt_pk_bf16_f32 v117, v118, v119
	v_cndmask_b32_e64 v119, v151, 0, s[0:1]
	v_cndmask_b32_e64 v118, v149, 0, s[0:1]
	v_pk_fma_f32 v[120:121], v[68:69], v[124:125], v[120:121]
	v_cndmask_b32_e64 v127, v146, 0, vcc
	v_pk_fma_f32 v[118:119], v[64:65], v[118:119], v[120:121]
	v_cndmask_b32_e64 v126, v144, 0, vcc
	v_mul_f32_e32 v120, 0xbfb8aa3b, v118
	v_exp_f32_e32 v124, v120
	v_mul_f32_e32 v120, 0xbfb8aa3b, v119
	v_exp_f32_e32 v125, v120
	v_pk_fma_f32 v[120:121], v[122:123], v[74:75], v[78:79]
	v_add_f32_e32 v122, 1.0, v124
	v_cndmask_b32_e64 v124, v145, 0, s[0:1]
	v_add_f32_e32 v123, 1.0, v125
	v_cndmask_b32_e64 v125, v147, 0, s[0:1]
	v_pk_fma_f32 v[120:121], v[70:71], v[126:127], v[120:121]
	v_rcp_f32_e32 v122, v122
	v_pk_fma_f32 v[120:121], v[66:67], v[124:125], v[120:121]
	v_rcp_f32_e32 v123, v123
	v_mul_f32_e32 v124, 0xbfb8aa3b, v120
	v_mul_f32_e32 v125, 0xbfb8aa3b, v121
	v_exp_f32_e32 v124, v124
	v_exp_f32_e32 v125, v125
	v_pk_mul_f32 v[118:119], v[118:119], v[122:123]
	v_add_f32_e32 v124, 1.0, v124
	v_add_f32_e32 v125, 1.0, v125
	v_rcp_f32_e32 v124, v124
	v_rcp_f32_e32 v125, v125
	v_pk_mul_f32 v[112:113], v[112:113], v[118:119]
	s_nop 0
	v_cvt_pk_bf16_f32 v118, v112, v113
	v_pk_mul_f32 v[112:113], v[120:121], v[124:125]
	s_nop 0
	v_pk_mul_f32 v[112:113], v[114:115], v[112:113]
	s_nop 0
	v_cvt_pk_bf16_f32 v119, v112, v113
	v_mov_b64_e32 v[112:113], s[60:61]
	v_mad_i64_i32 v[112:113], s[0:1], v205, s29, v[112:113]
	v_lshl_add_u64 v[112:113], v[180:181], 1, v[112:113]
	global_store_dwordx4 v[112:113], v[116:119], off
.LBB0_815:
	s_or_b64 exec, exec, s[26:27]
	v_add_u32_e32 v112, s21, v202
	v_mov_b32_dpp v140, v108 row_shr:1 row_mask:0xf bank_mask:0xf
	v_mov_b32_dpp v141, v108 row_shr:2 row_mask:0xf bank_mask:0xf
	v_mov_b32_dpp v142, v109 row_shr:1 row_mask:0xf bank_mask:0xf
	v_mov_b32_dpp v143, v109 row_shr:2 row_mask:0xf bank_mask:0xf
	v_mov_b32_dpp v136, v110 row_shr:1 row_mask:0xf bank_mask:0xf
	v_mov_b32_dpp v137, v110 row_shr:2 row_mask:0xf bank_mask:0xf
	v_mov_b32_dpp v138, v111 row_shr:1 row_mask:0xf bank_mask:0xf
	v_mov_b32_dpp v139, v111 row_shr:2 row_mask:0xf bank_mask:0xf
	v_mov_b32_dpp v132, v104 row_shr:1 row_mask:0xf bank_mask:0xf
	v_mov_b32_dpp v133, v104 row_shr:2 row_mask:0xf bank_mask:0xf
	v_mov_b32_dpp v134, v105 row_shr:1 row_mask:0xf bank_mask:0xf
	v_mov_b32_dpp v135, v105 row_shr:2 row_mask:0xf bank_mask:0xf
	v_mov_b32_dpp v128, v106 row_shr:1 row_mask:0xf bank_mask:0xf
	v_mov_b32_dpp v129, v106 row_shr:2 row_mask:0xf bank_mask:0xf
	v_mov_b32_dpp v130, v107 row_shr:1 row_mask:0xf bank_mask:0xf
	v_mov_b32_dpp v131, v107 row_shr:2 row_mask:0xf bank_mask:0xf
	v_cmp_gt_i32_e32 vcc, s28, v112
	s_and_saveexec_b64 s[26:27], vcc
	s_cbranch_execz .LBB0_817
	v_and_b32_e32 v113, 0x3fff, v112
	v_cmp_eq_u32_e32 vcc, 0, v113
	v_cmp_gt_u32_e64 s[0:1], 2, v113
	s_nop 0
	v_pk_fma_f32 v[108:109], v[108:109], v[92:93], v[96:97]
	v_cndmask_b32_e64 v117, v142, 0, vcc
	v_cndmask_b32_e64 v116, v140, 0, vcc
	v_cndmask_b32_e64 v115, v143, 0, s[0:1]
	v_cndmask_b32_e64 v114, v141, 0, s[0:1]
	v_pk_fma_f32 v[108:109], v[84:85], v[116:117], v[108:109]
	v_pk_fma_f32 v[110:111], v[110:111], v[94:95], v[98:99]
	v_pk_fma_f32 v[108:109], v[80:81], v[114:115], v[108:109]
	v_cndmask_b32_e64 v119, v138, 0, vcc
	v_mul_f32_e32 v113, 0xbfb8aa3b, v108
	v_exp_f32_e32 v113, v113
	v_mul_f32_e32 v114, 0xbfb8aa3b, v109
	v_exp_f32_e32 v115, v114
	v_cndmask_b32_e64 v118, v136, 0, vcc
	v_cndmask_b32_e64 v117, v139, 0, s[0:1]
	v_cndmask_b32_e64 v116, v137, 0, s[0:1]
	v_pk_fma_f32 v[110:111], v[86:87], v[118:119], v[110:111]
	v_add_f32_e32 v113, 1.0, v113
	v_pk_fma_f32 v[110:111], v[82:83], v[116:117], v[110:111]
	v_rcp_f32_e32 v114, v113
	v_add_f32_e32 v113, 1.0, v115
	v_mul_f32_e32 v115, 0xbfb8aa3b, v110
	v_exp_f32_e32 v116, v115
	v_mul_f32_e32 v115, 0xbfb8aa3b, v111
	v_exp_f32_e32 v117, v115
	v_rcp_f32_e32 v115, v113
	v_add_f32_e32 v113, 1.0, v116
	v_rcp_f32_e32 v116, v113
	v_add_f32_e32 v113, 1.0, v117
	v_rcp_f32_e32 v117, v113
	v_pk_mul_f32 v[108:109], v[108:109], v[114:115]
	v_pk_fma_f32 v[104:105], v[104:105], v[72:73], v[76:77]
	v_pk_mul_f32 v[100:101], v[100:101], v[108:109]
	v_pk_mul_f32 v[108:109], v[110:111], v[116:117]
	v_cvt_pk_bf16_f32 v100, v100, v101
	v_pk_mul_f32 v[102:103], v[102:103], v[108:109]
	v_cndmask_b32_e64 v109, v134, 0, vcc
	v_cndmask_b32_e64 v108, v132, 0, vcc
	v_cvt_pk_bf16_f32 v101, v102, v103
	v_cndmask_b32_e64 v103, v135, 0, s[0:1]
	v_cndmask_b32_e64 v102, v133, 0, s[0:1]
	v_pk_fma_f32 v[104:105], v[68:69], v[108:109], v[104:105]
	v_cndmask_b32_e64 v111, v130, 0, vcc
	v_pk_fma_f32 v[102:103], v[64:65], v[102:103], v[104:105]
	v_cndmask_b32_e64 v110, v128, 0, vcc
	v_mul_f32_e32 v104, 0xbfb8aa3b, v102
	v_exp_f32_e32 v108, v104
	v_mul_f32_e32 v104, 0xbfb8aa3b, v103
	v_exp_f32_e32 v109, v104
	v_pk_fma_f32 v[104:105], v[106:107], v[74:75], v[78:79]
	v_add_f32_e32 v106, 1.0, v108
	v_cndmask_b32_e64 v108, v129, 0, s[0:1]
	v_add_f32_e32 v107, 1.0, v109
	v_cndmask_b32_e64 v109, v131, 0, s[0:1]
	v_pk_fma_f32 v[104:105], v[70:71], v[110:111], v[104:105]
	v_rcp_f32_e32 v106, v106
	v_pk_fma_f32 v[104:105], v[66:67], v[108:109], v[104:105]
	v_rcp_f32_e32 v107, v107
	v_mul_f32_e32 v108, 0xbfb8aa3b, v104
	v_mul_f32_e32 v109, 0xbfb8aa3b, v105
	v_exp_f32_e32 v108, v108
	v_exp_f32_e32 v109, v109
	v_pk_mul_f32 v[102:103], v[102:103], v[106:107]
	v_add_f32_e32 v108, 1.0, v108
	v_add_f32_e32 v109, 1.0, v109
	v_rcp_f32_e32 v108, v108
	v_rcp_f32_e32 v109, v109
	v_pk_mul_f32 v[88:89], v[88:89], v[102:103]
	s_nop 0
	v_cvt_pk_bf16_f32 v102, v88, v89
	v_pk_mul_f32 v[88:89], v[104:105], v[108:109]
	s_nop 0
	v_pk_mul_f32 v[88:89], v[90:91], v[88:89]
	s_nop 0
	v_cvt_pk_bf16_f32 v103, v88, v89
	v_mov_b64_e32 v[88:89], s[60:61]
	v_mad_i64_i32 v[88:89], s[0:1], v112, s29, v[88:89]
	v_lshl_add_u64 v[88:89], v[180:181], 1, v[88:89]
	global_store_dwordx4 v[88:89], v[100:103], off
; __device__ __forceinline__ unsigned cvt_pk_bf16(float lo, float hi) { const f32x2_t v = {lo, hi}; return __builtin_bit_cast(unsigned, __builtin_convertvector(v, bf16x2_t)); }
; #define PG8_DPP(old, src, ctrl) __builtin_bit_cast(float, __builtin_amdgcn_update_dpp(__builtin_bit_cast(int, (float)(old)), __builtin_bit_cast(int, (float)(src)), (ctrl), 0xf, 0xf, false))
;     __device__ __forceinline__ void operator()(const f32x4 (&acc)[2][2][4][2], const Unit& u, int wr, int wc, int fr, int fq) const {
;     ...
;             const int gbase = u.pm * 248 + 62 * (2 * ai + wr) - 2;
;             float r1[2][4], r2[2][4];
; #pragma unroll
;             for (int n = 0; n < 2; ++n)
; #pragma unroll
;                 for (int x = 0; x < 4; ++x) { r1[n][x] = 0.f; r2[n][x] = 0.f; }
; #pragma unroll
;             for (int m = 0; m < 4; ++m) {
;                 const int rl = 16 * m + fr, g = gbase + rl, tt = g & 16383;
;                 unsigned pk[4];
; #pragma unroll
;                 for (int n = 0; n < 2; ++n) {
;                     float a[4];
; #pragma unroll
;                     for (int x = 0; x < 4; ++x) {
;                         const float uu = acc[ai][0][m][n][x];
;                         float p1 = PG8_DPP(r1[n][x], uu, 0x111);
;                         float p2 = PG8_DPP(r2[n][x], uu, 0x112);
;                         r1[n][x] = PG8_DPP(0.f, uu, 0x121); r2[n][x] = PG8_DPP(0.f, uu, 0x122);
;                         if (tt < 1) p1 = 0.f;
;                         if (tt < 2) p2 = 0.f;
;                         const float uc = bb[n][x] + w2[n][x] * uu + w1[n][x] * p1 + w0[n][x] * p2;
;                         const float sg = __builtin_amdgcn_rcpf(1.f + __builtin_amdgcn_exp2f(-1.44269504f * uc));
;                         a[x] = uc * sg * acc[ai][1][m][n][x];
;                     }
;                     pk[2 * n] = cvt_pk_bf16(a[0], a[1]); pk[2 * n + 1] = cvt_pk_bf16(a[2], a[3]);
;                 }
;                 if (rl >= 2 && g < Mrows) { u32x4 w; w.x = pk[0]; w.y = pk[1]; w.z = pk[2]; w.w = pk[3]; *(u32x4*)(O + (size_t)g * 2816 + col0) = w; }
.LBB0_817:
	s_or_b64 exec, exec, s[26:27]
	s_addk_i32 s21, 0x7c
	v_add_u32_e32 v112, s21, v182
	v_mov_b32_e32 v125, v161
	v_mov_b32_e32 v126, v161
	v_mov_b32_e32 v108, v161
	v_mov_b32_e32 v109, v161
	v_mov_b32_e32 v127, v161
	v_mov_b32_e32 v128, v161
	v_mov_b32_e32 v110, v161
	v_mov_b32_e32 v111, v161
	v_mov_b32_e32 v121, v161
	v_mov_b32_e32 v122, v161
	v_mov_b32_e32 v104, v161
	v_mov_b32_e32 v105, v161
	v_mov_b32_e32 v123, v161
	v_mov_b32_e32 v124, v161
	v_mov_b32_e32 v106, v161
	v_mov_b32_e32 v107, v161
	v_mov_b32_e32 v117, v161
	v_mov_b32_e32 v118, v161
	v_mov_b32_e32 v100, v161
	v_mov_b32_e32 v101, v161
	v_mov_b32_e32 v119, v161
	v_mov_b32_e32 v120, v161
	v_mov_b32_e32 v102, v161
	v_mov_b32_e32 v103, v161
	v_mov_b32_e32 v113, v161
	v_mov_b32_e32 v114, v161
	v_mov_b32_e32 v88, v161
	v_mov_b32_e32 v89, v161
	v_mov_b32_e32 v115, v161
	v_mov_b32_e32 v116, v161
	v_mov_b32_e32 v90, v161
	v_mov_b32_e32 v91, v161
	v_cmp_gt_i32_e32 vcc, s28, v112
	v_mov_b32_dpp v125, v60 row_shr:1 row_mask:0xf bank_mask:0xf
	v_mov_b32_dpp v126, v60 row_shr:2 row_mask:0xf bank_mask:0xf
	v_mov_b32_dpp v108, v60 row_ror:1 row_mask:0xf bank_mask:0xf
	v_mov_b32_dpp v109, v60 row_ror:2 row_mask:0xf bank_mask:0xf
	v_mov_b32_dpp v127, v61 row_shr:1 row_mask:0xf bank_mask:0xf
	v_mov_b32_dpp v128, v61 row_shr:2 row_mask:0xf bank_mask:0xf
	v_mov_b32_dpp v110, v61 row_ror:1 row_mask:0xf bank_mask:0xf
	v_mov_b32_dpp v111, v61 row_ror:2 row_mask:0xf bank_mask:0xf
	v_mov_b32_dpp v121, v62 row_shr:1 row_mask:0xf bank_mask:0xf
	v_mov_b32_dpp v122, v62 row_shr:2 row_mask:0xf bank_mask:0xf
	v_mov_b32_dpp v104, v62 row_ror:1 row_mask:0xf bank_mask:0xf
	v_mov_b32_dpp v105, v62 row_ror:2 row_mask:0xf bank_mask:0xf
	v_mov_b32_dpp v123, v63 row_shr:1 row_mask:0xf bank_mask:0xf
	v_mov_b32_dpp v124, v63 row_shr:2 row_mask:0xf bank_mask:0xf
	v_mov_b32_dpp v106, v63 row_ror:1 row_mask:0xf bank_mask:0xf
	v_mov_b32_dpp v107, v63 row_ror:2 row_mask:0xf bank_mask:0xf
	v_mov_b32_dpp v117, v56 row_shr:1 row_mask:0xf bank_mask:0xf
	v_mov_b32_dpp v118, v56 row_shr:2 row_mask:0xf bank_mask:0xf
	v_mov_b32_dpp v100, v56 row_ror:1 row_mask:0xf bank_mask:0xf
	v_mov_b32_dpp v101, v56 row_ror:2 row_mask:0xf bank_mask:0xf
	v_mov_b32_dpp v119, v57 row_shr:1 row_mask:0xf bank_mask:0xf
	v_mov_b32_dpp v120, v57 row_shr:2 row_mask:0xf bank_mask:0xf
	v_mov_b32_dpp v102, v57 row_ror:1 row_mask:0xf bank_mask:0xf
	v_mov_b32_dpp v103, v57 row_ror:2 row_mask:0xf bank_mask:0xf
	v_mov_b32_dpp v113, v58 row_shr:1 row_mask:0xf bank_mask:0xf
	v_mov_b32_dpp v114, v58 row_shr:2 row_mask:0xf bank_mask:0xf
	v_mov_b32_dpp v88, v58 row_ror:1 row_mask:0xf bank_mask:0xf
	v_mov_b32_dpp v89, v58 row_ror:2 row_mask:0xf bank_mask:0xf
	v_mov_b32_dpp v115, v59 row_shr:1 row_mask:0xf bank_mask:0xf
	v_mov_b32_dpp v116, v59 row_shr:2 row_mask:0xf bank_mask:0xf
	v_mov_b32_dpp v90, v59 row_ror:1 row_mask:0xf bank_mask:0xf
	v_mov_b32_dpp v91, v59 row_ror:2 row_mask:0xf bank_mask:0xf
	s_and_b64 s[0:1], s[4:5], vcc
	s_and_saveexec_b64 s[26:27], s[0:1]
	s_cbranch_execz .LBB0_819
	v_and_b32_e32 v130, 0x3fff, v112
	v_cmp_gt_u32_e64 s[0:1], 2, v130
	v_cmp_eq_u32_e32 vcc, 0, v130
	s_nop 0
	v_pk_fma_f32 v[60:61], v[60:61], v[92:93], v[96:97]
	v_cndmask_b32_e64 v129, v128, 0, s[0:1]
	v_cndmask_b32_e64 v128, v126, 0, s[0:1]
	v_cndmask_b32_e64 v127, v127, 0, vcc
	v_cndmask_b32_e64 v126, v125, 0, vcc
	v_pk_fma_f32 v[60:61], v[84:85], v[126:127], v[60:61]
	v_pk_fma_f32 v[62:63], v[62:63], v[94:95], v[98:99]
	v_pk_fma_f32 v[60:61], v[80:81], v[128:129], v[60:61]
	v_cndmask_b32_e64 v123, v123, 0, vcc
	v_mul_f32_e32 v125, 0xbfb8aa3b, v60
	v_exp_f32_e32 v125, v125
	v_mul_f32_e32 v126, 0xbfb8aa3b, v61
	v_exp_f32_e32 v127, v126
	v_pk_fma_f32 v[56:57], v[56:57], v[72:73], v[76:77]
	v_add_f32_e32 v125, 1.0, v125
	v_rcp_f32_e32 v126, v125
	v_cndmask_b32_e64 v125, v124, 0, s[0:1]
	v_cndmask_b32_e64 v124, v122, 0, s[0:1]
	v_cndmask_b32_e64 v122, v121, 0, vcc
	v_pk_fma_f32 v[62:63], v[86:87], v[122:123], v[62:63]
	v_add_f32_e32 v127, 1.0, v127
	v_pk_fma_f32 v[62:63], v[82:83], v[124:125], v[62:63]
	v_rcp_f32_e32 v127, v127
	v_mul_f32_e32 v121, 0xbfb8aa3b, v62
	v_exp_f32_e32 v121, v121
	v_mul_f32_e32 v122, 0xbfb8aa3b, v63
	v_exp_f32_e32 v123, v122
	v_pk_mul_f32 v[60:61], v[60:61], v[126:127]
	v_add_f32_e32 v121, 1.0, v121
	v_rcp_f32_e32 v122, v121
	v_add_f32_e32 v121, 1.0, v123
	v_rcp_f32_e32 v123, v121
	v_pk_mul_f32 v[52:53], v[52:53], v[60:61]
	v_pk_mul_f32 v[60:61], v[62:63], v[122:123]
	s_nop 0
	v_pk_mul_f32 v[54:55], v[54:55], v[60:61]
	v_cndmask_b32_e64 v61, v119, 0, vcc
	v_cndmask_b32_e64 v60, v117, 0, vcc
	v_cvt_pk_bf16_f32 v52, v52, v53
	v_cvt_pk_bf16_f32 v53, v54, v55
	v_cndmask_b32_e64 v55, v120, 0, s[0:1]
	v_cndmask_b32_e64 v54, v118, 0, s[0:1]
	v_pk_fma_f32 v[56:57], v[68:69], v[60:61], v[56:57]
	v_cndmask_b32_e64 v63, v115, 0, vcc
	v_pk_fma_f32 v[54:55], v[64:65], v[54:55], v[56:57]
	v_cndmask_b32_e64 v62, v113, 0, vcc
	v_mul_f32_e32 v56, 0xbfb8aa3b, v54
	v_exp_f32_e32 v60, v56
	v_mul_f32_e32 v56, 0xbfb8aa3b, v55
	v_exp_f32_e32 v61, v56
	v_pk_fma_f32 v[56:57], v[58:59], v[74:75], v[78:79]
	v_add_f32_e32 v58, 1.0, v60
	v_cndmask_b32_e64 v60, v114, 0, s[0:1]
	v_add_f32_e32 v59, 1.0, v61
	v_cndmask_b32_e64 v61, v116, 0, s[0:1]
	v_pk_fma_f32 v[56:57], v[70:71], v[62:63], v[56:57]
	v_rcp_f32_e32 v58, v58
	v_pk_fma_f32 v[56:57], v[66:67], v[60:61], v[56:57]
	v_rcp_f32_e32 v59, v59
	v_mul_f32_e32 v60, 0xbfb8aa3b, v56
	v_mul_f32_e32 v61, 0xbfb8aa3b, v57
	v_exp_f32_e32 v60, v60
	v_exp_f32_e32 v61, v61
	v_pk_mul_f32 v[54:55], v[54:55], v[58:59]
	v_add_f32_e32 v60, 1.0, v60
	v_add_f32_e32 v61, 1.0, v61
	v_rcp_f32_e32 v60, v60
	v_rcp_f32_e32 v61, v61
	v_pk_mul_f32 v[48:49], v[48:49], v[54:55]
	s_nop 0
	v_cvt_pk_bf16_f32 v54, v48, v49
	v_pk_mul_f32 v[48:49], v[56:57], v[60:61]
	s_nop 0
	v_pk_mul_f32 v[48:49], v[50:51], v[48:49]
	s_nop 0
	v_cvt_pk_bf16_f32 v55, v48, v49
	v_mov_b64_e32 v[48:49], s[60:61]
	v_mad_i64_i32 v[48:49], s[0:1], v112, s29, v[48:49]
	v_lshl_add_u64 v[48:49], v[180:181], 1, v[48:49]
	global_store_dwordx4 v[48:49], v[52:55], off
; __device__ __forceinline__ unsigned cvt_pk_bf16(float lo, float hi) { const f32x2_t v = {lo, hi}; return __builtin_bit_cast(unsigned, __builtin_convertvector(v, bf16x2_t)); }
; #define PG8_DPP(old, src, ctrl) __builtin_bit_cast(float, __builtin_amdgcn_update_dpp(__builtin_bit_cast(int, (float)(old)), __builtin_bit_cast(int, (float)(src)), (ctrl), 0xf, 0xf, false))
;     __device__ __forceinline__ void operator()(const f32x4 (&acc)[2][2][4][2], const Unit& u, int wr, int wc, int fr, int fq) const {
;     ...
;             for (int m = 0; m < 4; ++m) {
;                 const int rl = 16 * m + fr, g = gbase + rl, tt = g & 16383;
;                 unsigned pk[4];
; #pragma unroll
;                 for (int n = 0; n < 2; ++n) {
;                     float a[4];
; #pragma unroll
;                     for (int x = 0; x < 4; ++x) {
;                         const float uu = acc[ai][0][m][n][x];
;                         float p1 = PG8_DPP(r1[n][x], uu, 0x111);
;                         float p2 = PG8_DPP(r2[n][x], uu, 0x112);
;                         r1[n][x] = PG8_DPP(0.f, uu, 0x121); r2[n][x] = PG8_DPP(0.f, uu, 0x122);
;                         if (tt < 1) p1 = 0.f;
;                         if (tt < 2) p2 = 0.f;
;                         const float uc = bb[n][x] + w2[n][x] * uu + w1[n][x] * p1 + w0[n][x] * p2;
;                         const float sg = __builtin_amdgcn_rcpf(1.f + __builtin_amdgcn_exp2f(-1.44269504f * uc));
;                         a[x] = uc * sg * acc[ai][1][m][n][x];
;                     }
;                     pk[2 * n] = cvt_pk_bf16(a[0], a[1]); pk[2 * n + 1] = cvt_pk_bf16(a[2], a[3]);
;                 }
;                 if (rl >= 2 && g < Mrows) { u32x4 w; w.x = pk[0]; w.y = pk[1]; w.z = pk[2]; w.w = pk[3]; *(u32x4*)(O + (size_t)g * 2816 + col0) = w; }
.LBB0_819:
	s_or_b64 exec, exec, s[26:27]
	v_add_u32_e32 v112, s21, v184
	v_mov_b32_e32 v60, v161
	v_mov_b32_e32 v61, v161
	v_mov_b32_e32 v62, v161
	v_mov_b32_e32 v63, v161
	v_mov_b32_e32 v56, v161
	v_mov_b32_e32 v57, v161
	v_mov_b32_e32 v58, v161
	v_mov_b32_e32 v59, v161
	v_mov_b32_e32 v52, v161
	v_mov_b32_e32 v53, v161
	v_mov_b32_e32 v54, v161
	v_mov_b32_e32 v55, v161
	v_mov_b32_e32 v48, v161
	v_mov_b32_e32 v49, v161
	v_mov_b32_e32 v50, v161
	v_mov_b32_e32 v51, v161
	v_mov_b32_dpp v108, v44 row_shr:1 row_mask:0xf bank_mask:0xf
	v_mov_b32_dpp v109, v44 row_shr:2 row_mask:0xf bank_mask:0xf
	v_mov_b32_dpp v60, v44 row_ror:1 row_mask:0xf bank_mask:0xf
	v_mov_b32_dpp v61, v44 row_ror:2 row_mask:0xf bank_mask:0xf
	v_mov_b32_dpp v110, v45 row_shr:1 row_mask:0xf bank_mask:0xf
	v_mov_b32_dpp v111, v45 row_shr:2 row_mask:0xf bank_mask:0xf
	v_mov_b32_dpp v62, v45 row_ror:1 row_mask:0xf bank_mask:0xf
	v_mov_b32_dpp v63, v45 row_ror:2 row_mask:0xf bank_mask:0xf
	v_mov_b32_dpp v104, v46 row_shr:1 row_mask:0xf bank_mask:0xf
	v_mov_b32_dpp v105, v46 row_shr:2 row_mask:0xf bank_mask:0xf
	v_mov_b32_dpp v56, v46 row_ror:1 row_mask:0xf bank_mask:0xf
	v_mov_b32_dpp v57, v46 row_ror:2 row_mask:0xf bank_mask:0xf
	v_mov_b32_dpp v106, v47 row_shr:1 row_mask:0xf bank_mask:0xf
	v_mov_b32_dpp v107, v47 row_shr:2 row_mask:0xf bank_mask:0xf
	v_mov_b32_dpp v58, v47 row_ror:1 row_mask:0xf bank_mask:0xf
	v_mov_b32_dpp v59, v47 row_ror:2 row_mask:0xf bank_mask:0xf
	v_mov_b32_dpp v100, v40 row_shr:1 row_mask:0xf bank_mask:0xf
	v_mov_b32_dpp v101, v40 row_shr:2 row_mask:0xf bank_mask:0xf
	v_mov_b32_dpp v52, v40 row_ror:1 row_mask:0xf bank_mask:0xf
	v_mov_b32_dpp v53, v40 row_ror:2 row_mask:0xf bank_mask:0xf
	v_mov_b32_dpp v102, v41 row_shr:1 row_mask:0xf bank_mask:0xf
	v_mov_b32_dpp v103, v41 row_shr:2 row_mask:0xf bank_mask:0xf
	v_mov_b32_dpp v54, v41 row_ror:1 row_mask:0xf bank_mask:0xf
	v_mov_b32_dpp v55, v41 row_ror:2 row_mask:0xf bank_mask:0xf
	v_mov_b32_dpp v88, v42 row_shr:1 row_mask:0xf bank_mask:0xf
	v_mov_b32_dpp v89, v42 row_shr:2 row_mask:0xf bank_mask:0xf
	v_mov_b32_dpp v48, v42 row_ror:1 row_mask:0xf bank_mask:0xf
	v_mov_b32_dpp v49, v42 row_ror:2 row_mask:0xf bank_mask:0xf
	v_mov_b32_dpp v90, v43 row_shr:1 row_mask:0xf bank_mask:0xf
	v_mov_b32_dpp v91, v43 row_shr:2 row_mask:0xf bank_mask:0xf
	v_mov_b32_dpp v50, v43 row_ror:1 row_mask:0xf bank_mask:0xf
	v_mov_b32_dpp v51, v43 row_ror:2 row_mask:0xf bank_mask:0xf
	v_cmp_gt_i32_e32 vcc, s28, v112
	s_and_saveexec_b64 s[26:27], vcc
	s_cbranch_execz .LBB0_821
	v_and_b32_e32 v113, 0x3fff, v112
	v_cmp_gt_u32_e64 s[0:1], 2, v113
	v_cmp_eq_u32_e32 vcc, 0, v113
	s_nop 0
	v_pk_fma_f32 v[44:45], v[44:45], v[92:93], v[96:97]
	v_cndmask_b32_e64 v114, v109, 0, s[0:1]
	v_cndmask_b32_e64 v109, v110, 0, vcc
	v_cndmask_b32_e64 v108, v108, 0, vcc
	v_cndmask_b32_e64 v115, v111, 0, s[0:1]
	v_pk_fma_f32 v[44:45], v[84:85], v[108:109], v[44:45]
	v_pk_fma_f32 v[46:47], v[46:47], v[94:95], v[98:99]
	v_cndmask_b32_e64 v110, v105, 0, s[0:1]
	v_cndmask_b32_e64 v105, v106, 0, vcc
	v_cndmask_b32_e64 v104, v104, 0, vcc
	v_pk_fma_f32 v[44:45], v[80:81], v[114:115], v[44:45]
	v_cndmask_b32_e64 v111, v107, 0, s[0:1]
	v_pk_fma_f32 v[46:47], v[86:87], v[104:105], v[46:47]
	v_mul_f32_e32 v108, 0xbfb8aa3b, v44
	v_mul_f32_e32 v109, 0xbfb8aa3b, v45
	v_pk_fma_f32 v[46:47], v[82:83], v[110:111], v[46:47]
	v_exp_f32_e32 v108, v108
	v_exp_f32_e32 v109, v109
	v_mul_f32_e32 v104, 0xbfb8aa3b, v46
	v_mul_f32_e32 v105, 0xbfb8aa3b, v47
	v_exp_f32_e32 v104, v104
	v_exp_f32_e32 v105, v105
	v_add_f32_e32 v108, 1.0, v108
	v_add_f32_e32 v109, 1.0, v109
	v_rcp_f32_e32 v108, v108
	v_rcp_f32_e32 v109, v109
	v_add_f32_e32 v104, 1.0, v104
	v_add_f32_e32 v105, 1.0, v105
	v_rcp_f32_e32 v104, v104
	v_rcp_f32_e32 v105, v105
	v_pk_mul_f32 v[44:45], v[44:45], v[108:109]
	v_pk_fma_f32 v[40:41], v[40:41], v[72:73], v[76:77]
	v_pk_mul_f32 v[36:37], v[36:37], v[44:45]
	v_pk_mul_f32 v[44:45], v[46:47], v[104:105]
	v_cvt_pk_bf16_f32 v36, v36, v37
	v_pk_mul_f32 v[38:39], v[38:39], v[44:45]
	v_cndmask_b32_e64 v45, v102, 0, vcc
	v_cndmask_b32_e64 v44, v100, 0, vcc
	v_cvt_pk_bf16_f32 v37, v38, v39
	v_cndmask_b32_e64 v39, v103, 0, s[0:1]
	v_cndmask_b32_e64 v38, v101, 0, s[0:1]
	v_pk_fma_f32 v[40:41], v[68:69], v[44:45], v[40:41]
	v_cndmask_b32_e64 v47, v90, 0, vcc
	v_pk_fma_f32 v[38:39], v[64:65], v[38:39], v[40:41]
	v_cndmask_b32_e64 v46, v88, 0, vcc
	v_mul_f32_e32 v40, 0xbfb8aa3b, v38
	v_exp_f32_e32 v44, v40
	v_mul_f32_e32 v40, 0xbfb8aa3b, v39
	v_exp_f32_e32 v45, v40
	v_pk_fma_f32 v[40:41], v[42:43], v[74:75], v[78:79]
	v_add_f32_e32 v42, 1.0, v44
	v_cndmask_b32_e64 v44, v89, 0, s[0:1]
	v_add_f32_e32 v43, 1.0, v45
	v_cndmask_b32_e64 v45, v91, 0, s[0:1]
	v_pk_fma_f32 v[40:41], v[70:71], v[46:47], v[40:41]
	v_rcp_f32_e32 v42, v42
	v_pk_fma_f32 v[40:41], v[66:67], v[44:45], v[40:41]
	v_rcp_f32_e32 v43, v43
	v_mul_f32_e32 v44, 0xbfb8aa3b, v40
	v_mul_f32_e32 v45, 0xbfb8aa3b, v41
	v_exp_f32_e32 v44, v44
	v_exp_f32_e32 v45, v45
	v_pk_mul_f32 v[38:39], v[38:39], v[42:43]
	v_add_f32_e32 v44, 1.0, v44
	v_add_f32_e32 v45, 1.0, v45
	v_rcp_f32_e32 v44, v44
	v_rcp_f32_e32 v45, v45
	v_pk_mul_f32 v[32:33], v[32:33], v[38:39]
	s_nop 0
	v_cvt_pk_bf16_f32 v38, v32, v33
	v_pk_mul_f32 v[32:33], v[40:41], v[44:45]
	s_nop 0
	v_pk_mul_f32 v[32:33], v[34:35], v[32:33]
	s_nop 0
	v_cvt_pk_bf16_f32 v39, v32, v33
	v_mov_b64_e32 v[32:33], s[60:61]
	v_mad_i64_i32 v[32:33], s[0:1], v112, s29, v[32:33]
	v_lshl_add_u64 v[32:33], v[180:181], 1, v[32:33]
	global_store_dwordx4 v[32:33], v[36:39], off
; __device__ __forceinline__ unsigned cvt_pk_bf16(float lo, float hi) { const f32x2_t v = {lo, hi}; return __builtin_bit_cast(unsigned, __builtin_convertvector(v, bf16x2_t)); }
; #define PG8_DPP(old, src, ctrl) __builtin_bit_cast(float, __builtin_amdgcn_update_dpp(__builtin_bit_cast(int, (float)(old)), __builtin_bit_cast(int, (float)(src)), (ctrl), 0xf, 0xf, false))
;     __device__ __forceinline__ void operator()(const f32x4 (&acc)[2][2][4][2], const Unit& u, int wr, int wc, int fr, int fq) const {
;     ...
;             for (int m = 0; m < 4; ++m) {
;                 const int rl = 16 * m + fr, g = gbase + rl, tt = g & 16383;
;                 unsigned pk[4];
; #pragma unroll
;                 for (int n = 0; n < 2; ++n) {
;                     float a[4];
; #pragma unroll
;                     for (int x = 0; x < 4; ++x) {
;                         const float uu = acc[ai][0][m][n][x];
;                         float p1 = PG8_DPP(r1[n][x], uu, 0x111);
;                         float p2 = PG8_DPP(r2[n][x], uu, 0x112);
;                         r1[n][x] = PG8_DPP(0.f, uu, 0x121); r2[n][x] = PG8_DPP(0.f, uu, 0x122);
;                         if (tt < 1) p1 = 0.f;
;                         if (tt < 2) p2 = 0.f;
;                         const float uc = bb[n][x] + w2[n][x] * uu + w1[n][x] * p1 + w0[n][x] * p2;
;                         const float sg = __builtin_amdgcn_rcpf(1.f + __builtin_amdgcn_exp2f(-1.44269504f * uc));
;                         a[x] = uc * sg * acc[ai][1][m][n][x];
;                     }
;                     pk[2 * n] = cvt_pk_bf16(a[0], a[1]); pk[2 * n + 1] = cvt_pk_bf16(a[2], a[3]);
;                 }
;                 if (rl >= 2 && g < Mrows) { u32x4 w; w.x = pk[0]; w.y = pk[1]; w.z = pk[2]; w.w = pk[3]; *(u32x4*)(O + (size_t)g * 2816 + col0) = w; }
.LBB0_821:
	s_or_b64 exec, exec, s[26:27]
	v_add_u32_e32 v88, s21, v185
	v_mov_b32_e32 v44, v161
	v_mov_b32_e32 v45, v161
	v_mov_b32_e32 v46, v161
	v_mov_b32_e32 v47, v161
	v_mov_b32_e32 v40, v161
	v_mov_b32_e32 v41, v161
	v_mov_b32_e32 v42, v161
	v_mov_b32_e32 v43, v161
	v_mov_b32_e32 v36, v161
	v_mov_b32_e32 v37, v161
	v_mov_b32_e32 v38, v161
	v_mov_b32_e32 v39, v161
	v_mov_b32_e32 v32, v161
	v_mov_b32_e32 v33, v161
	v_mov_b32_e32 v34, v161
	v_mov_b32_e32 v35, v161
	v_mov_b32_dpp v60, v28 row_shr:1 row_mask:0xf bank_mask:0xf
	v_mov_b32_dpp v61, v28 row_shr:2 row_mask:0xf bank_mask:0xf
	v_mov_b32_dpp v44, v28 row_ror:1 row_mask:0xf bank_mask:0xf
	v_mov_b32_dpp v45, v28 row_ror:2 row_mask:0xf bank_mask:0xf
	v_mov_b32_dpp v62, v29 row_shr:1 row_mask:0xf bank_mask:0xf
	v_mov_b32_dpp v63, v29 row_shr:2 row_mask:0xf bank_mask:0xf
	v_mov_b32_dpp v46, v29 row_ror:1 row_mask:0xf bank_mask:0xf
	v_mov_b32_dpp v47, v29 row_ror:2 row_mask:0xf bank_mask:0xf
	v_mov_b32_dpp v56, v30 row_shr:1 row_mask:0xf bank_mask:0xf
	v_mov_b32_dpp v57, v30 row_shr:2 row_mask:0xf bank_mask:0xf
	v_mov_b32_dpp v40, v30 row_ror:1 row_mask:0xf bank_mask:0xf
	v_mov_b32_dpp v41, v30 row_ror:2 row_mask:0xf bank_mask:0xf
	v_mov_b32_dpp v58, v31 row_shr:1 row_mask:0xf bank_mask:0xf
	v_mov_b32_dpp v59, v31 row_shr:2 row_mask:0xf bank_mask:0xf
	v_mov_b32_dpp v42, v31 row_ror:1 row_mask:0xf bank_mask:0xf
	v_mov_b32_dpp v43, v31 row_ror:2 row_mask:0xf bank_mask:0xf
	v_mov_b32_dpp v52, v24 row_shr:1 row_mask:0xf bank_mask:0xf
	v_mov_b32_dpp v53, v24 row_shr:2 row_mask:0xf bank_mask:0xf
	v_mov_b32_dpp v36, v24 row_ror:1 row_mask:0xf bank_mask:0xf
	v_mov_b32_dpp v37, v24 row_ror:2 row_mask:0xf bank_mask:0xf
	v_mov_b32_dpp v54, v25 row_shr:1 row_mask:0xf bank_mask:0xf
	v_mov_b32_dpp v55, v25 row_shr:2 row_mask:0xf bank_mask:0xf
	v_mov_b32_dpp v38, v25 row_ror:1 row_mask:0xf bank_mask:0xf
	v_mov_b32_dpp v39, v25 row_ror:2 row_mask:0xf bank_mask:0xf
	v_mov_b32_dpp v48, v26 row_shr:1 row_mask:0xf bank_mask:0xf
	v_mov_b32_dpp v49, v26 row_shr:2 row_mask:0xf bank_mask:0xf
	v_mov_b32_dpp v32, v26 row_ror:1 row_mask:0xf bank_mask:0xf
	v_mov_b32_dpp v33, v26 row_ror:2 row_mask:0xf bank_mask:0xf
	v_mov_b32_dpp v50, v27 row_shr:1 row_mask:0xf bank_mask:0xf
	v_mov_b32_dpp v51, v27 row_shr:2 row_mask:0xf bank_mask:0xf
	v_mov_b32_dpp v34, v27 row_ror:1 row_mask:0xf bank_mask:0xf
	v_mov_b32_dpp v35, v27 row_ror:2 row_mask:0xf bank_mask:0xf
	v_cmp_gt_i32_e32 vcc, s28, v88
	s_and_saveexec_b64 s[26:27], vcc
	s_cbranch_execz .LBB0_823
	v_and_b32_e32 v89, 0x3fff, v88
	v_cmp_gt_u32_e64 s[0:1], 2, v89
	v_cmp_eq_u32_e32 vcc, 0, v89
	s_nop 0
	v_pk_fma_f32 v[28:29], v[28:29], v[92:93], v[96:97]
	v_cndmask_b32_e64 v90, v61, 0, s[0:1]
	v_cndmask_b32_e64 v61, v62, 0, vcc
	v_cndmask_b32_e64 v60, v60, 0, vcc
	v_cndmask_b32_e64 v91, v63, 0, s[0:1]
	v_pk_fma_f32 v[28:29], v[84:85], v[60:61], v[28:29]
	v_pk_fma_f32 v[30:31], v[30:31], v[94:95], v[98:99]
	v_cndmask_b32_e64 v62, v57, 0, s[0:1]
	v_cndmask_b32_e64 v57, v58, 0, vcc
	v_cndmask_b32_e64 v56, v56, 0, vcc
	v_pk_fma_f32 v[28:29], v[80:81], v[90:91], v[28:29]
	v_cndmask_b32_e64 v63, v59, 0, s[0:1]
	v_pk_fma_f32 v[30:31], v[86:87], v[56:57], v[30:31]
	v_mul_f32_e32 v60, 0xbfb8aa3b, v28
	v_mul_f32_e32 v61, 0xbfb8aa3b, v29
	v_pk_fma_f32 v[30:31], v[82:83], v[62:63], v[30:31]
	v_exp_f32_e32 v60, v60
	v_exp_f32_e32 v61, v61
	v_mul_f32_e32 v56, 0xbfb8aa3b, v30
	v_mul_f32_e32 v57, 0xbfb8aa3b, v31
	v_exp_f32_e32 v56, v56
	v_exp_f32_e32 v57, v57
	v_add_f32_e32 v60, 1.0, v60
	v_add_f32_e32 v61, 1.0, v61
	v_rcp_f32_e32 v60, v60
	v_rcp_f32_e32 v61, v61
	v_add_f32_e32 v56, 1.0, v56
	v_add_f32_e32 v57, 1.0, v57
	v_rcp_f32_e32 v56, v56
	v_rcp_f32_e32 v57, v57
	v_pk_mul_f32 v[28:29], v[28:29], v[60:61]
	v_pk_fma_f32 v[24:25], v[24:25], v[72:73], v[76:77]
	v_pk_mul_f32 v[20:21], v[20:21], v[28:29]
	v_pk_mul_f32 v[28:29], v[30:31], v[56:57]
	v_cvt_pk_bf16_f32 v20, v20, v21
	v_pk_mul_f32 v[22:23], v[22:23], v[28:29]
	v_cndmask_b32_e64 v29, v54, 0, vcc
	v_cndmask_b32_e64 v28, v52, 0, vcc
	v_cvt_pk_bf16_f32 v21, v22, v23
	v_cndmask_b32_e64 v23, v55, 0, s[0:1]
	v_cndmask_b32_e64 v22, v53, 0, s[0:1]
	v_pk_fma_f32 v[24:25], v[68:69], v[28:29], v[24:25]
	v_cndmask_b32_e64 v31, v50, 0, vcc
	v_pk_fma_f32 v[22:23], v[64:65], v[22:23], v[24:25]
	v_cndmask_b32_e64 v30, v48, 0, vcc
	v_mul_f32_e32 v24, 0xbfb8aa3b, v22
	v_exp_f32_e32 v28, v24
	v_mul_f32_e32 v24, 0xbfb8aa3b, v23
	v_exp_f32_e32 v29, v24
	v_pk_fma_f32 v[24:25], v[26:27], v[74:75], v[78:79]
	v_add_f32_e32 v26, 1.0, v28
	v_cndmask_b32_e64 v28, v49, 0, s[0:1]
	v_add_f32_e32 v27, 1.0, v29
	v_cndmask_b32_e64 v29, v51, 0, s[0:1]
	v_pk_fma_f32 v[24:25], v[70:71], v[30:31], v[24:25]
	v_rcp_f32_e32 v26, v26
	v_pk_fma_f32 v[24:25], v[66:67], v[28:29], v[24:25]
	v_rcp_f32_e32 v27, v27
	v_mul_f32_e32 v28, 0xbfb8aa3b, v24
	v_mul_f32_e32 v29, 0xbfb8aa3b, v25
	v_exp_f32_e32 v28, v28
	v_exp_f32_e32 v29, v29
	v_pk_mul_f32 v[22:23], v[22:23], v[26:27]
	v_add_f32_e32 v28, 1.0, v28
	v_add_f32_e32 v29, 1.0, v29
	v_rcp_f32_e32 v28, v28
	v_rcp_f32_e32 v29, v29
	v_pk_mul_f32 v[16:17], v[16:17], v[22:23]
	s_nop 0
	v_cvt_pk_bf16_f32 v22, v16, v17
	v_pk_mul_f32 v[16:17], v[24:25], v[28:29]
	s_nop 0
	v_pk_mul_f32 v[16:17], v[18:19], v[16:17]
	s_nop 0
	v_cvt_pk_bf16_f32 v23, v16, v17
	v_mov_b64_e32 v[16:17], s[60:61]
	v_mad_i64_i32 v[16:17], s[0:1], v88, s29, v[16:17]
	v_lshl_add_u64 v[16:17], v[180:181], 1, v[16:17]
	global_store_dwordx4 v[16:17], v[20:23], off
; __device__ __forceinline__ unsigned cvt_pk_bf16(float lo, float hi) { const f32x2_t v = {lo, hi}; return __builtin_bit_cast(unsigned, __builtin_convertvector(v, bf16x2_t)); }
; #define PG8_DPP(old, src, ctrl) __builtin_bit_cast(float, __builtin_amdgcn_update_dpp(__builtin_bit_cast(int, (float)(old)), __builtin_bit_cast(int, (float)(src)), (ctrl), 0xf, 0xf, false))
;     __device__ __forceinline__ void operator()(const f32x4 (&acc)[2][2][4][2], const Unit& u, int wr, int wc, int fr, int fq) const {
;     ...
;             for (int m = 0; m < 4; ++m) {
;                 const int rl = 16 * m + fr, g = gbase + rl, tt = g & 16383;
;                 unsigned pk[4];
; #pragma unroll
;                 for (int n = 0; n < 2; ++n) {
;                     float a[4];
; #pragma unroll
;                     for (int x = 0; x < 4; ++x) {
;                         const float uu = acc[ai][0][m][n][x];
;                         float p1 = PG8_DPP(r1[n][x], uu, 0x111);
;                         float p2 = PG8_DPP(r2[n][x], uu, 0x112);
;                         r1[n][x] = PG8_DPP(0.f, uu, 0x121); r2[n][x] = PG8_DPP(0.f, uu, 0x122);
;                         if (tt < 1) p1 = 0.f;
;                         if (tt < 2) p2 = 0.f;
;                         const float uc = bb[n][x] + w2[n][x] * uu + w1[n][x] * p1 + w0[n][x] * p2;
;                         const float sg = __builtin_amdgcn_rcpf(1.f + __builtin_amdgcn_exp2f(-1.44269504f * uc));
;                         a[x] = uc * sg * acc[ai][1][m][n][x];
;                     }
;                     pk[2 * n] = cvt_pk_bf16(a[0], a[1]); pk[2 * n + 1] = cvt_pk_bf16(a[2], a[3]);
;                 }
;                 if (rl >= 2 && g < Mrows) { u32x4 w; w.x = pk[0]; w.y = pk[1]; w.z = pk[2]; w.w = pk[3]; *(u32x4*)(O + (size_t)g * 2816 + col0) = w; }
.LBB0_823:
	s_or_b64 exec, exec, s[26:27]
	v_add_u32_e32 v16, s21, v202
	v_mov_b32_dpp v44, v12 row_shr:1 row_mask:0xf bank_mask:0xf
	v_mov_b32_dpp v45, v12 row_shr:2 row_mask:0xf bank_mask:0xf
	v_mov_b32_dpp v46, v13 row_shr:1 row_mask:0xf bank_mask:0xf
	v_mov_b32_dpp v47, v13 row_shr:2 row_mask:0xf bank_mask:0xf
	v_mov_b32_dpp v40, v14 row_shr:1 row_mask:0xf bank_mask:0xf
	v_mov_b32_dpp v41, v14 row_shr:2 row_mask:0xf bank_mask:0xf
	v_mov_b32_dpp v42, v15 row_shr:1 row_mask:0xf bank_mask:0xf
	v_mov_b32_dpp v43, v15 row_shr:2 row_mask:0xf bank_mask:0xf
	v_mov_b32_dpp v36, v8 row_shr:1 row_mask:0xf bank_mask:0xf
	v_mov_b32_dpp v37, v8 row_shr:2 row_mask:0xf bank_mask:0xf
	v_mov_b32_dpp v38, v9 row_shr:1 row_mask:0xf bank_mask:0xf
	v_mov_b32_dpp v39, v9 row_shr:2 row_mask:0xf bank_mask:0xf
	v_mov_b32_dpp v32, v10 row_shr:1 row_mask:0xf bank_mask:0xf
	v_mov_b32_dpp v33, v10 row_shr:2 row_mask:0xf bank_mask:0xf
	v_mov_b32_dpp v34, v11 row_shr:1 row_mask:0xf bank_mask:0xf
	v_mov_b32_dpp v35, v11 row_shr:2 row_mask:0xf bank_mask:0xf
	v_cmp_gt_i32_e32 vcc, s28, v16
	s_and_saveexec_b64 s[26:27], vcc
	s_cbranch_execz .LBB0_825
	v_and_b32_e32 v17, 0x3fff, v16
	v_cmp_eq_u32_e32 vcc, 0, v17
	v_cmp_gt_u32_e64 s[0:1], 2, v17
	s_nop 0
	v_pk_fma_f32 v[12:13], v[12:13], v[92:93], v[96:97]
	v_cndmask_b32_e64 v21, v46, 0, vcc
	v_cndmask_b32_e64 v20, v44, 0, vcc
	v_cndmask_b32_e64 v19, v47, 0, s[0:1]
	v_cndmask_b32_e64 v18, v45, 0, s[0:1]
	v_pk_fma_f32 v[12:13], v[84:85], v[20:21], v[12:13]
	v_pk_fma_f32 v[14:15], v[14:15], v[94:95], v[98:99]
	v_pk_fma_f32 v[12:13], v[80:81], v[18:19], v[12:13]
	v_cndmask_b32_e64 v23, v42, 0, vcc
	v_mul_f32_e32 v17, 0xbfb8aa3b, v12
	v_exp_f32_e32 v17, v17
	v_mul_f32_e32 v18, 0xbfb8aa3b, v13
	v_exp_f32_e32 v19, v18
	v_cndmask_b32_e64 v22, v40, 0, vcc
	v_cndmask_b32_e64 v21, v43, 0, s[0:1]
	v_cndmask_b32_e64 v20, v41, 0, s[0:1]
	v_pk_fma_f32 v[14:15], v[86:87], v[22:23], v[14:15]
	v_add_f32_e32 v17, 1.0, v17
	v_pk_fma_f32 v[14:15], v[82:83], v[20:21], v[14:15]
	v_rcp_f32_e32 v18, v17
	v_add_f32_e32 v17, 1.0, v19
	v_mul_f32_e32 v19, 0xbfb8aa3b, v14
	v_exp_f32_e32 v20, v19
	v_mul_f32_e32 v19, 0xbfb8aa3b, v15
	v_exp_f32_e32 v21, v19
	v_rcp_f32_e32 v19, v17
	v_add_f32_e32 v17, 1.0, v20
	v_rcp_f32_e32 v20, v17
	v_add_f32_e32 v17, 1.0, v21
	v_rcp_f32_e32 v21, v17
	v_pk_mul_f32 v[12:13], v[12:13], v[18:19]
	v_pk_fma_f32 v[8:9], v[8:9], v[72:73], v[76:77]
	v_pk_mul_f32 v[4:5], v[4:5], v[12:13]
	v_pk_mul_f32 v[12:13], v[14:15], v[20:21]
	v_cvt_pk_bf16_f32 v4, v4, v5
	v_pk_mul_f32 v[6:7], v[6:7], v[12:13]
	v_cndmask_b32_e64 v13, v38, 0, vcc
	v_cndmask_b32_e64 v12, v36, 0, vcc
	v_cvt_pk_bf16_f32 v5, v6, v7
	v_cndmask_b32_e64 v7, v39, 0, s[0:1]
	v_cndmask_b32_e64 v6, v37, 0, s[0:1]
	v_pk_fma_f32 v[8:9], v[68:69], v[12:13], v[8:9]
	v_cndmask_b32_e64 v15, v34, 0, vcc
	v_pk_fma_f32 v[6:7], v[64:65], v[6:7], v[8:9]
	v_cndmask_b32_e64 v14, v32, 0, vcc
	v_mul_f32_e32 v8, 0xbfb8aa3b, v6
	v_exp_f32_e32 v12, v8
	v_mul_f32_e32 v8, 0xbfb8aa3b, v7
	v_exp_f32_e32 v13, v8
	v_pk_fma_f32 v[8:9], v[10:11], v[74:75], v[78:79]
	v_add_f32_e32 v10, 1.0, v12
	v_cndmask_b32_e64 v12, v33, 0, s[0:1]
	v_add_f32_e32 v11, 1.0, v13
	v_cndmask_b32_e64 v13, v35, 0, s[0:1]
	v_pk_fma_f32 v[8:9], v[70:71], v[14:15], v[8:9]
	v_rcp_f32_e32 v10, v10
	v_pk_fma_f32 v[8:9], v[66:67], v[12:13], v[8:9]
	v_rcp_f32_e32 v11, v11
	v_mul_f32_e32 v12, 0xbfb8aa3b, v8
	v_mul_f32_e32 v13, 0xbfb8aa3b, v9
	v_exp_f32_e32 v12, v12
	v_exp_f32_e32 v13, v13
	v_pk_mul_f32 v[6:7], v[6:7], v[10:11]
	v_add_f32_e32 v12, 1.0, v12
	v_add_f32_e32 v13, 1.0, v13
	v_rcp_f32_e32 v12, v12
	v_rcp_f32_e32 v13, v13
	v_pk_mul_f32 v[0:1], v[0:1], v[6:7]
	s_nop 0
	v_cvt_pk_bf16_f32 v6, v0, v1
	v_pk_mul_f32 v[0:1], v[8:9], v[12:13]
	s_nop 0
	v_pk_mul_f32 v[0:1], v[2:3], v[0:1]
	s_nop 0
	v_cvt_pk_bf16_f32 v7, v0, v1
	v_mov_b64_e32 v[0:1], s[60:61]
	v_mad_i64_i32 v[0:1], s[0:1], v16, s29, v[0:1]
	v_lshl_add_u64 v[0:1], v[180:181], 1, v[0:1]
	global_store_dwordx4 v[0:1], v[4:7], off
